# k48 + non-temporal (nt) HH tile stores in the FF1 epilogue (never re-read in that phase: keep the weights and A rows in the L2)
# baseline (speedup 1.0000x reference)
.LBB0_859:
	s_add_u32 s98, s10, 0x80
	s_addc_u32 s99, s11, 0
	v_lshl_add_u64 v[250:251], s[98:99], 0, v[136:137]
	s_add_i32 m0, s25, 0xc000
	s_nop 0
	global_load_lds_dwordx4 v[250:251], off
	v_lshl_add_u64 v[250:251], s[98:99], 0, v[138:139]
	s_add_i32 m0, s25, 0xe000
	s_nop 0
	global_load_lds_dwordx4 v[250:251], off
	v_lshl_add_u32 v152, s80, 8, v146
	v_lshl_or_b32 v144, s81, 8, v148
	v_ashrrev_i32_e32 v153, 31, v152
	v_max_f32_e32 v120, 0, v120
	v_ashrrev_i32_e32 v145, 31, v144
	v_lshlrev_b64 v[154:155], 13, v[152:153]
	v_max_f32_e32 v121, 0, v121
	v_max_f32_e32 v122, 0, v122
	v_max_f32_e32 v123, 0, v123
	v_lshl_add_u64 v[154:155], s[16:17], 0, v[154:155]
	v_lshlrev_b64 v[156:157], 1, v[144:145]
	v_max_f32_e32 v124, 0, v124
	v_mul_f32_e32 v120, v120, v120
	v_max_f32_e32 v125, 0, v125
	v_max_f32_e32 v126, 0, v126
	v_max_f32_e32 v127, 0, v127
	v_max_f32_e32 v112, 0, v112
	v_lshl_add_u64 v[144:145], v[154:155], 0, v[156:157]
	v_mul_f32_e32 v121, v121, v121
	v_mul_f32_e32 v122, v122, v122
	v_mul_f32_e32 v123, v123, v123
	v_cvt_pk_bf16_f32 v120, v120, v121
	v_max_f32_e32 v113, 0, v113
	v_max_f32_e32 v114, 0, v114
	v_mul_f32_e32 v124, v124, v124
	v_mul_f32_e32 v125, v125, v125
	v_mul_f32_e32 v126, v126, v126
	v_mul_f32_e32 v127, v127, v127
	v_cvt_pk_bf16_f32 v121, v122, v123
	v_cvt_pk_bf16_f32 v122, v124, v125
	v_cvt_pk_bf16_f32 v123, v126, v127
	global_store_dwordx4 v[144:145], v[120:123], off nt
	s_nop 1
	v_mul_f32_e32 v120, v112, v112
	v_max_f32_e32 v112, 0, v117
	v_max_f32_e32 v116, 0, v116
	v_mul_f32_e32 v117, v113, v113
	v_max_f32_e32 v113, 0, v118
	v_mul_f32_e32 v118, v114, v114
	v_max_f32_e32 v114, 0, v119
	v_max_f32_e32 v115, 0, v115
	v_mul_f32_e32 v112, v112, v112
	v_mul_f32_e32 v116, v116, v116
	v_mul_f32_e32 v113, v113, v113
	v_mul_f32_e32 v114, v114, v114
	v_mul_f32_e32 v115, v115, v115
	v_cvt_pk_bf16_f32 v112, v116, v112
	v_max_f32_e32 v104, 0, v104
	v_cvt_pk_bf16_f32 v113, v113, v114
	v_cvt_pk_bf16_f32 v114, v120, v117
	v_cvt_pk_bf16_f32 v115, v118, v115
	global_store_dwordx4 v[144:145], v[112:115], off offset:256 nt
	s_nop 1
	v_max_f32_e32 v105, 0, v105
	v_or_b32_e32 v112, 16, v152
	v_max_f32_e32 v106, 0, v106
	v_ashrrev_i32_e32 v113, 31, v112
	v_mul_f32_e32 v114, v104, v104
	v_max_f32_e32 v104, 0, v109
	v_lshlrev_b64 v[112:113], 13, v[112:113]
	v_max_f32_e32 v108, 0, v108
	v_mul_f32_e32 v109, v105, v105
	v_max_f32_e32 v105, 0, v110
	v_mul_f32_e32 v110, v106, v106
	v_max_f32_e32 v106, 0, v111
	v_max_f32_e32 v107, 0, v107
	v_lshl_add_u64 v[112:113], s[16:17], 0, v[112:113]
	v_mul_f32_e32 v104, v104, v104
	v_max_f32_e32 v96, 0, v96
	v_lshl_add_u64 v[112:113], v[112:113], 0, v[156:157]
	v_mul_f32_e32 v108, v108, v108
	v_mul_f32_e32 v105, v105, v105
	v_mul_f32_e32 v106, v106, v106
	v_mul_f32_e32 v107, v107, v107
	v_cvt_pk_bf16_f32 v104, v108, v104
	v_max_f32_e32 v97, 0, v97
	v_max_f32_e32 v98, 0, v98
	v_cvt_pk_bf16_f32 v105, v105, v106
	v_cvt_pk_bf16_f32 v106, v114, v109
	v_cvt_pk_bf16_f32 v107, v110, v107
	global_store_dwordx4 v[112:113], v[104:107], off nt
	s_nop 1
	v_mul_f32_e32 v104, v96, v96
	v_max_f32_e32 v96, 0, v101
	v_max_f32_e32 v100, 0, v100
	v_mul_f32_e32 v101, v97, v97
	v_max_f32_e32 v97, 0, v102
	v_mul_f32_e32 v102, v98, v98
	v_max_f32_e32 v98, 0, v103
	v_max_f32_e32 v99, 0, v99
	v_mul_f32_e32 v96, v96, v96
	v_mul_f32_e32 v100, v100, v100
	v_mul_f32_e32 v97, v97, v97
	v_mul_f32_e32 v98, v98, v98
	v_mul_f32_e32 v99, v99, v99
	v_cvt_pk_bf16_f32 v96, v100, v96
	v_max_f32_e32 v88, 0, v88
	v_cvt_pk_bf16_f32 v97, v97, v98
	v_cvt_pk_bf16_f32 v98, v104, v101
	v_cvt_pk_bf16_f32 v99, v102, v99
	global_store_dwordx4 v[112:113], v[96:99], off offset:256 nt
	s_nop 1
	v_max_f32_e32 v89, 0, v89
	v_or_b32_e32 v96, 32, v152
	v_max_f32_e32 v90, 0, v90
	v_ashrrev_i32_e32 v97, 31, v96
	v_mul_f32_e32 v98, v88, v88
	v_max_f32_e32 v88, 0, v93
	v_lshlrev_b64 v[96:97], 13, v[96:97]
	v_max_f32_e32 v92, 0, v92
	v_mul_f32_e32 v93, v89, v89
	v_max_f32_e32 v89, 0, v94
	v_mul_f32_e32 v94, v90, v90
	v_max_f32_e32 v90, 0, v95
	v_max_f32_e32 v91, 0, v91
	v_lshl_add_u64 v[96:97], s[16:17], 0, v[96:97]
	v_mul_f32_e32 v88, v88, v88
	v_max_f32_e32 v80, 0, v80
	v_lshl_add_u64 v[96:97], v[96:97], 0, v[156:157]
	v_mul_f32_e32 v92, v92, v92
	v_mul_f32_e32 v89, v89, v89
	v_mul_f32_e32 v90, v90, v90
	v_mul_f32_e32 v91, v91, v91
	v_cvt_pk_bf16_f32 v88, v92, v88
	v_max_f32_e32 v81, 0, v81
	v_max_f32_e32 v82, 0, v82
	v_cvt_pk_bf16_f32 v89, v89, v90
	v_cvt_pk_bf16_f32 v90, v98, v93
	v_cvt_pk_bf16_f32 v91, v94, v91
	global_store_dwordx4 v[96:97], v[88:91], off nt
	s_nop 1
	v_mul_f32_e32 v88, v80, v80
	v_max_f32_e32 v80, 0, v85
	v_max_f32_e32 v84, 0, v84
	v_mul_f32_e32 v85, v81, v81
	v_max_f32_e32 v81, 0, v86
	v_mul_f32_e32 v86, v82, v82
	v_max_f32_e32 v82, 0, v87
	v_max_f32_e32 v83, 0, v83
	v_mul_f32_e32 v80, v80, v80
	v_mul_f32_e32 v84, v84, v84
	v_mul_f32_e32 v81, v81, v81
	v_mul_f32_e32 v82, v82, v82
	v_mul_f32_e32 v83, v83, v83
	v_cvt_pk_bf16_f32 v80, v84, v80
	v_max_f32_e32 v72, 0, v72
	v_cvt_pk_bf16_f32 v81, v81, v82
	v_cvt_pk_bf16_f32 v82, v88, v85
	v_cvt_pk_bf16_f32 v83, v86, v83
	global_store_dwordx4 v[96:97], v[80:83], off offset:256 nt
	s_nop 1
	v_max_f32_e32 v73, 0, v73
	v_or_b32_e32 v80, 48, v152
	v_max_f32_e32 v74, 0, v74
	v_ashrrev_i32_e32 v81, 31, v80
	v_mul_f32_e32 v82, v72, v72
	v_max_f32_e32 v72, 0, v77
	v_lshlrev_b64 v[80:81], 13, v[80:81]
	v_max_f32_e32 v76, 0, v76
	v_mul_f32_e32 v77, v73, v73
	v_max_f32_e32 v73, 0, v78
	v_mul_f32_e32 v78, v74, v74
	v_max_f32_e32 v74, 0, v79
	v_max_f32_e32 v75, 0, v75
	v_lshl_add_u64 v[80:81], s[16:17], 0, v[80:81]
	v_mul_f32_e32 v72, v72, v72
	v_max_f32_e32 v64, 0, v64
	v_max_f32_e32 v65, 0, v65
	v_max_f32_e32 v66, 0, v66
	v_lshl_add_u64 v[80:81], v[80:81], 0, v[156:157]
	v_mul_f32_e32 v76, v76, v76
	v_mul_f32_e32 v73, v73, v73
	v_mul_f32_e32 v74, v74, v74
	v_mul_f32_e32 v75, v75, v75
	v_cvt_pk_bf16_f32 v72, v76, v72
	v_cvt_pk_bf16_f32 v73, v73, v74
	v_cvt_pk_bf16_f32 v74, v82, v77
	v_cvt_pk_bf16_f32 v75, v78, v75
	global_store_dwordx4 v[80:81], v[72:75], off nt
	v_max_f32_e32 v68, 0, v68
	v_max_f32_e32 v67, 0, v67
	v_mul_f32_e32 v72, v64, v64
	v_max_f32_e32 v64, 0, v69
	v_mul_f32_e32 v69, v65, v65
	v_max_f32_e32 v65, 0, v70
	v_mul_f32_e32 v70, v66, v66
	v_max_f32_e32 v66, 0, v71
	v_mul_f32_e32 v64, v64, v64
	v_mul_f32_e32 v65, v65, v65
	v_mul_f32_e32 v66, v66, v66
	v_max_f32_e32 v56, 0, v56
	v_mul_f32_e32 v68, v68, v68
	v_mul_f32_e32 v67, v67, v67
	v_cvt_pk_bf16_f32 v64, v68, v64
	v_cvt_pk_bf16_f32 v65, v65, v66
	v_cvt_pk_bf16_f32 v66, v72, v69
	v_max_f32_e32 v57, 0, v57
	v_max_f32_e32 v58, 0, v58
	v_cvt_pk_bf16_f32 v67, v70, v67
	global_store_dwordx4 v[80:81], v[64:67], off offset:256 nt
	s_nop 1
	v_max_f32_e32 v60, 0, v60
	v_mul_f32_e32 v66, v56, v56
	v_max_f32_e32 v56, 0, v61
	v_mul_f32_e32 v61, v57, v57
	v_max_f32_e32 v57, 0, v62
	v_mul_f32_e32 v62, v58, v58
	v_max_f32_e32 v58, 0, v63
	v_mul_f32_e32 v60, v60, v60
	v_mul_f32_e32 v56, v56, v56
	v_max_f32_e32 v59, 0, v59
	v_mul_f32_e32 v57, v57, v57
	v_mul_f32_e32 v58, v58, v58
	v_cvt_pk_bf16_f32 v56, v60, v56
	v_add_co_u32_e32 v60, vcc, s69, v144
	v_max_f32_e32 v48, 0, v48
	v_max_f32_e32 v49, 0, v49
	v_max_f32_e32 v50, 0, v50
	v_mul_f32_e32 v59, v59, v59
	v_cvt_pk_bf16_f32 v57, v57, v58
	v_cvt_pk_bf16_f32 v58, v66, v61
	v_addc_co_u32_e32 v61, vcc, 0, v145, vcc
	v_cvt_pk_bf16_f32 v59, v62, v59
	global_store_dwordx4 v[60:61], v[56:59], off nt
	v_max_f32_e32 v52, 0, v52
	v_max_f32_e32 v51, 0, v51
	v_mul_f32_e32 v56, v48, v48
	v_max_f32_e32 v48, 0, v53
	v_mul_f32_e32 v53, v49, v49
	v_max_f32_e32 v49, 0, v54
	v_mul_f32_e32 v54, v50, v50
	v_max_f32_e32 v50, 0, v55
	v_mul_f32_e32 v48, v48, v48
	v_mul_f32_e32 v49, v49, v49
	v_mul_f32_e32 v50, v50, v50
	v_max_f32_e32 v40, 0, v40
	v_lshl_add_u64 v[64:65], v[144:145], 0, s[50:51]
	v_mul_f32_e32 v52, v52, v52
	v_mul_f32_e32 v51, v51, v51
	v_cvt_pk_bf16_f32 v48, v52, v48
	v_cvt_pk_bf16_f32 v49, v49, v50
	v_cvt_pk_bf16_f32 v50, v56, v53
	v_max_f32_e32 v41, 0, v41
	v_max_f32_e32 v42, 0, v42
	v_cvt_pk_bf16_f32 v51, v54, v51
	global_store_dwordx4 v[64:65], v[48:51], off offset:256 nt
	s_nop 1
	v_max_f32_e32 v44, 0, v44
	v_mul_f32_e32 v50, v40, v40
	v_max_f32_e32 v40, 0, v45
	v_mul_f32_e32 v45, v41, v41
	v_max_f32_e32 v41, 0, v46
	v_mul_f32_e32 v46, v42, v42
	v_max_f32_e32 v42, 0, v47
	v_mul_f32_e32 v44, v44, v44
	v_mul_f32_e32 v40, v40, v40
	v_max_f32_e32 v43, 0, v43
	v_mul_f32_e32 v41, v41, v41
	v_mul_f32_e32 v42, v42, v42
	v_cvt_pk_bf16_f32 v40, v44, v40
	v_add_co_u32_e32 v44, vcc, s71, v144
	v_max_f32_e32 v32, 0, v32
	v_max_f32_e32 v33, 0, v33
	v_max_f32_e32 v34, 0, v34
	v_mul_f32_e32 v43, v43, v43
	v_cvt_pk_bf16_f32 v41, v41, v42
	v_cvt_pk_bf16_f32 v42, v50, v45
	v_addc_co_u32_e32 v45, vcc, 0, v145, vcc
	v_cvt_pk_bf16_f32 v43, v46, v43
	global_store_dwordx4 v[44:45], v[40:43], off nt
	v_max_f32_e32 v36, 0, v36
	v_max_f32_e32 v35, 0, v35
	v_mul_f32_e32 v40, v32, v32
	v_max_f32_e32 v32, 0, v37
	v_mul_f32_e32 v37, v33, v33
	v_max_f32_e32 v33, 0, v38
	v_mul_f32_e32 v38, v34, v34
	v_max_f32_e32 v34, 0, v39
	v_mul_f32_e32 v32, v32, v32
	v_mul_f32_e32 v33, v33, v33
	v_mul_f32_e32 v34, v34, v34
	v_max_f32_e32 v24, 0, v24
	v_lshl_add_u64 v[48:49], v[144:145], 0, s[52:53]
	v_mul_f32_e32 v36, v36, v36
	v_mul_f32_e32 v35, v35, v35
	v_cvt_pk_bf16_f32 v32, v36, v32
	v_cvt_pk_bf16_f32 v33, v33, v34
	v_cvt_pk_bf16_f32 v34, v40, v37
	v_max_f32_e32 v25, 0, v25
	v_max_f32_e32 v26, 0, v26
	v_cvt_pk_bf16_f32 v35, v38, v35
	global_store_dwordx4 v[48:49], v[32:35], off offset:256 nt
	s_nop 1
	v_max_f32_e32 v28, 0, v28
	v_mul_f32_e32 v34, v24, v24
	v_max_f32_e32 v24, 0, v29
	v_mul_f32_e32 v29, v25, v25
	v_max_f32_e32 v25, 0, v30
	v_mul_f32_e32 v30, v26, v26
	v_max_f32_e32 v26, 0, v31
	v_mul_f32_e32 v28, v28, v28
	v_mul_f32_e32 v24, v24, v24
	v_max_f32_e32 v27, 0, v27
	v_mul_f32_e32 v25, v25, v25
	v_mul_f32_e32 v26, v26, v26
	v_cvt_pk_bf16_f32 v24, v28, v24
	v_add_co_u32_e32 v28, vcc, s72, v144
	v_max_f32_e32 v16, 0, v16
	v_max_f32_e32 v17, 0, v17
	v_max_f32_e32 v18, 0, v18
	v_mul_f32_e32 v27, v27, v27
	v_cvt_pk_bf16_f32 v25, v25, v26
	v_cvt_pk_bf16_f32 v26, v34, v29
	v_addc_co_u32_e32 v29, vcc, 0, v145, vcc
	v_cvt_pk_bf16_f32 v27, v30, v27
	global_store_dwordx4 v[28:29], v[24:27], off nt
	v_max_f32_e32 v20, 0, v20
	v_max_f32_e32 v19, 0, v19
	v_mul_f32_e32 v24, v16, v16
	v_max_f32_e32 v16, 0, v21
	v_mul_f32_e32 v21, v17, v17
	v_max_f32_e32 v17, 0, v22
	v_mul_f32_e32 v22, v18, v18
	v_max_f32_e32 v18, 0, v23
	v_mul_f32_e32 v16, v16, v16
	v_mul_f32_e32 v17, v17, v17
	v_mul_f32_e32 v18, v18, v18
	v_max_f32_e32 v8, 0, v8
	v_lshl_add_u64 v[32:33], v[144:145], 0, s[54:55]
	v_mul_f32_e32 v20, v20, v20
	v_mul_f32_e32 v19, v19, v19
	v_cvt_pk_bf16_f32 v16, v20, v16
	v_cvt_pk_bf16_f32 v17, v17, v18
	v_cvt_pk_bf16_f32 v18, v24, v21
	v_max_f32_e32 v9, 0, v9
	v_max_f32_e32 v10, 0, v10
	v_cvt_pk_bf16_f32 v19, v22, v19
	global_store_dwordx4 v[32:33], v[16:19], off offset:256 nt
	s_nop 1
	v_max_f32_e32 v12, 0, v12
	v_mul_f32_e32 v18, v8, v8
	v_max_f32_e32 v8, 0, v13
	v_mul_f32_e32 v13, v9, v9
	v_max_f32_e32 v9, 0, v14
	v_mul_f32_e32 v14, v10, v10
	v_max_f32_e32 v10, 0, v15
	v_mul_f32_e32 v12, v12, v12
	v_mul_f32_e32 v8, v8, v8
	v_max_f32_e32 v11, 0, v11
	v_mul_f32_e32 v9, v9, v9
	v_mul_f32_e32 v10, v10, v10
	v_cvt_pk_bf16_f32 v8, v12, v8
	v_add_co_u32_e32 v12, vcc, s75, v144
	v_max_f32_e32 v0, 0, v0
	v_max_f32_e32 v1, 0, v1
	v_max_f32_e32 v2, 0, v2
	v_mul_f32_e32 v11, v11, v11
	v_cvt_pk_bf16_f32 v9, v9, v10
	v_cvt_pk_bf16_f32 v10, v18, v13
	v_addc_co_u32_e32 v13, vcc, 0, v145, vcc
	v_cvt_pk_bf16_f32 v11, v14, v11
	global_store_dwordx4 v[12:13], v[8:11], off nt
	v_max_f32_e32 v3, 0, v3
	v_max_f32_e32 v4, 0, v4
	v_mul_f32_e32 v8, v0, v0
	v_max_f32_e32 v0, 0, v5
	v_mul_f32_e32 v5, v1, v1
	v_max_f32_e32 v1, 0, v6
	v_mul_f32_e32 v6, v2, v2
	v_max_f32_e32 v2, 0, v7
	v_lshl_add_u64 v[16:17], v[144:145], 0, s[56:57]
	v_mul_f32_e32 v0, v0, v0
	v_mul_f32_e32 v1, v1, v1
	v_mul_f32_e32 v2, v2, v2
	v_mul_f32_e32 v3, v3, v3
	s_and_b64 vcc, exec, s[8:9]
	s_mov_b64 s[8:9], -1
	v_mul_f32_e32 v4, v4, v4
	v_cvt_pk_bf16_f32 v0, v4, v0
	v_cvt_pk_bf16_f32 v1, v1, v2
	v_cvt_pk_bf16_f32 v2, v8, v5
	v_cvt_pk_bf16_f32 v3, v6, v3
	global_store_dwordx4 v[16:17], v[0:3], off offset:256 nt
	s_cbranch_vccnz .LBB0_843
	s_andn2_b64 vcc, exec, s[42:43]
	s_cbranch_vccnz .LBB0_842
	s_barrier
	s_branch .LBB0_842
